# GEMM K-loop heads aligned to 64 bytes
# speedup vs baseline: 1.0021x; 1.0021x over previous
.LBB0_168:
	s_ashr_i32 s43, s42, 31
	s_lshl_b64 s[36:37], s[42:43], 20
	s_add_u32 s44, s20, s36
	s_addc_u32 s45, s21, s37
	s_and_b64 s[36:37], s[38:39], exec
	s_cselect_b32 s36, s45, s51
	s_cselect_b32 s37, s44, s50
	s_ashr_i32 s41, s40, 31
	s_lshl_b64 s[46:47], s[40:41], 15
	s_add_u32 s46, s33, s46
	s_addc_u32 s47, s56, s47
	s_and_b64 s[54:55], s[38:39], exec
	s_cselect_b32 s41, s47, s35
	s_cselect_b32 s43, s46, s34
	s_add_u32 s71, s34, 0x2c0000
	s_addc_u32 s76, s35, 0
	s_add_u32 s50, s50, 0x80080
	v_mov_b32_e32 v4, 0
	s_addc_u32 s51, s51, 0
	s_mov_b32 s77, -2
	v_mov_b32_e32 v5, v4
	v_mov_b32_e32 v6, v4
	v_mov_b32_e32 v7, v4
	v_mov_b32_e32 v8, v4
	v_mov_b32_e32 v9, v4
	v_mov_b32_e32 v10, v4
	v_mov_b32_e32 v11, v4
	v_mov_b32_e32 v20, v4
	v_mov_b32_e32 v21, v4
	v_mov_b32_e32 v22, v4
	v_mov_b32_e32 v23, v4
	v_mov_b32_e32 v24, v4
	v_mov_b32_e32 v25, v4
	v_mov_b32_e32 v26, v4
	v_mov_b32_e32 v27, v4
	v_mov_b32_e32 v36, v4
	v_mov_b32_e32 v37, v4
	v_mov_b32_e32 v38, v4
	v_mov_b32_e32 v39, v4
	v_mov_b32_e32 v40, v4
	v_mov_b32_e32 v41, v4
	v_mov_b32_e32 v42, v4
	v_mov_b32_e32 v43, v4
	v_mov_b32_e32 v52, v4
	v_mov_b32_e32 v53, v4
	v_mov_b32_e32 v54, v4
	v_mov_b32_e32 v55, v4
	v_mov_b32_e32 v56, v4
	v_mov_b32_e32 v57, v4
	v_mov_b32_e32 v58, v4
	v_mov_b32_e32 v59, v4
	v_mov_b32_e32 v12, v4
	v_mov_b32_e32 v13, v4
	v_mov_b32_e32 v14, v4
	v_mov_b32_e32 v15, v4
	v_mov_b32_e32 v16, v4
	v_mov_b32_e32 v17, v4
	v_mov_b32_e32 v18, v4
	v_mov_b32_e32 v19, v4
	v_mov_b32_e32 v28, v4
	v_mov_b32_e32 v29, v4
	v_mov_b32_e32 v30, v4
	v_mov_b32_e32 v31, v4
	v_mov_b32_e32 v32, v4
	v_mov_b32_e32 v33, v4
	v_mov_b32_e32 v34, v4
	v_mov_b32_e32 v35, v4
	v_mov_b32_e32 v44, v4
	v_mov_b32_e32 v45, v4
	v_mov_b32_e32 v46, v4
	v_mov_b32_e32 v47, v4
	v_mov_b32_e32 v48, v4
	v_mov_b32_e32 v49, v4
	v_mov_b32_e32 v50, v4
	v_mov_b32_e32 v51, v4
	v_mov_b32_e32 v60, v4
	v_mov_b32_e32 v61, v4
	v_mov_b32_e32 v62, v4
	v_mov_b32_e32 v63, v4
	v_mov_b32_e32 v64, v4
	v_mov_b32_e32 v65, v4
	v_mov_b32_e32 v66, v4
	v_mov_b32_e32 v67, v4
	v_mov_b32_e32 v68, v4
	v_mov_b32_e32 v69, v4
	v_mov_b32_e32 v70, v4
	v_mov_b32_e32 v71, v4
	v_mov_b32_e32 v72, v4
	v_mov_b32_e32 v73, v4
	v_mov_b32_e32 v74, v4
	v_mov_b32_e32 v75, v4
	v_mov_b32_e32 v84, v4
	v_mov_b32_e32 v85, v4
	v_mov_b32_e32 v86, v4
	v_mov_b32_e32 v87, v4
	v_mov_b32_e32 v88, v4
	v_mov_b32_e32 v89, v4
	v_mov_b32_e32 v90, v4
	v_mov_b32_e32 v91, v4
	v_mov_b32_e32 v100, v4
	v_mov_b32_e32 v101, v4
	v_mov_b32_e32 v102, v4
	v_mov_b32_e32 v103, v4
	v_mov_b32_e32 v104, v4
	v_mov_b32_e32 v105, v4
	v_mov_b32_e32 v106, v4
	v_mov_b32_e32 v107, v4
	v_mov_b32_e32 v116, v4
	v_mov_b32_e32 v117, v4
	v_mov_b32_e32 v118, v4
	v_mov_b32_e32 v119, v4
	v_mov_b32_e32 v120, v4
	v_mov_b32_e32 v121, v4
	v_mov_b32_e32 v122, v4
	v_mov_b32_e32 v123, v4
	v_mov_b32_e32 v76, v4
	v_mov_b32_e32 v77, v4
	v_mov_b32_e32 v78, v4
	v_mov_b32_e32 v79, v4
	v_mov_b32_e32 v80, v4
	v_mov_b32_e32 v81, v4
	v_mov_b32_e32 v82, v4
	v_mov_b32_e32 v83, v4
	v_mov_b32_e32 v92, v4
	v_mov_b32_e32 v93, v4
	v_mov_b32_e32 v94, v4
	v_mov_b32_e32 v95, v4
	v_mov_b32_e32 v96, v4
	v_mov_b32_e32 v97, v4
	v_mov_b32_e32 v98, v4
	v_mov_b32_e32 v99, v4
	v_mov_b32_e32 v108, v4
	v_mov_b32_e32 v109, v4
	v_mov_b32_e32 v110, v4
	v_mov_b32_e32 v111, v4
	v_mov_b32_e32 v112, v4
	v_mov_b32_e32 v113, v4
	v_mov_b32_e32 v114, v4
	v_mov_b32_e32 v115, v4
	v_mov_b32_e32 v124, v4
	v_mov_b32_e32 v125, v4
	v_mov_b32_e32 v126, v4
	v_mov_b32_e32 v127, v4
	v_mov_b32_e32 v128, v4
	v_mov_b32_e32 v129, v4
	v_mov_b32_e32 v130, v4
	v_mov_b32_e32 v131, v4
	.p2alignl 6, 3212836864

.LBB0_242:
	s_ashr_i32 s57, s56, 31
	s_lshl_b64 s[36:37], s[56:57], 20
	s_add_u32 s58, s20, s36
	s_addc_u32 s59, s21, s37
	s_and_b64 s[36:37], s[42:43], exec
	s_cselect_b32 s36, s59, s45
	s_cselect_b32 s37, s58, s44
	s_ashr_i32 s55, s54, 31
	s_lshl_b64 s[46:47], s[54:55], 15
	s_add_u32 s60, s19, s46
	s_addc_u32 s61, s33, s47
	s_and_b64 s[46:47], s[42:43], exec
	s_cselect_b32 s55, s61, s35
	s_cselect_b32 s57, s60, s34
	s_add_u32 s63, s34, 0xe0000
	s_addc_u32 vcc_lo, s35, 0
	s_add_u32 s44, s44, 0x80080
	v_mov_b32_e32 v4, 0
	s_addc_u32 s45, s45, 0
	s_mov_b32 vcc_hi, -2
	v_mov_b32_e32 v5, v4
	v_mov_b32_e32 v6, v4
	v_mov_b32_e32 v7, v4
	v_mov_b32_e32 v8, v4
	v_mov_b32_e32 v9, v4
	v_mov_b32_e32 v10, v4
	v_mov_b32_e32 v11, v4
	v_mov_b32_e32 v20, v4
	v_mov_b32_e32 v21, v4
	v_mov_b32_e32 v22, v4
	v_mov_b32_e32 v23, v4
	v_mov_b32_e32 v24, v4
	v_mov_b32_e32 v25, v4
	v_mov_b32_e32 v26, v4
	v_mov_b32_e32 v27, v4
	v_mov_b32_e32 v36, v4
	v_mov_b32_e32 v37, v4
	s_waitcnt lgkmcnt(0)
	v_mov_b32_e32 v38, v4
	v_mov_b32_e32 v39, v4
	v_mov_b32_e32 v40, v4
	v_mov_b32_e32 v41, v4
	v_mov_b32_e32 v42, v4
	v_mov_b32_e32 v43, v4
	v_mov_b32_e32 v52, v4
	v_mov_b32_e32 v53, v4
	v_mov_b32_e32 v54, v4
	v_mov_b32_e32 v55, v4
	v_mov_b32_e32 v56, v4
	v_mov_b32_e32 v57, v4
	v_mov_b32_e32 v58, v4
	v_mov_b32_e32 v59, v4
	v_mov_b32_e32 v12, v4
	v_mov_b32_e32 v13, v4
	v_mov_b32_e32 v14, v4
	v_mov_b32_e32 v15, v4
	v_mov_b32_e32 v16, v4
	v_mov_b32_e32 v17, v4
	v_mov_b32_e32 v18, v4
	v_mov_b32_e32 v19, v4
	v_mov_b32_e32 v28, v4
	v_mov_b32_e32 v29, v4
	v_mov_b32_e32 v30, v4
	v_mov_b32_e32 v31, v4
	v_mov_b32_e32 v32, v4
	v_mov_b32_e32 v33, v4
	v_mov_b32_e32 v34, v4
	v_mov_b32_e32 v35, v4
	v_mov_b32_e32 v44, v4
	v_mov_b32_e32 v45, v4
	v_mov_b32_e32 v46, v4
	v_mov_b32_e32 v47, v4
	v_mov_b32_e32 v48, v4
	v_mov_b32_e32 v49, v4
	v_mov_b32_e32 v50, v4
	v_mov_b32_e32 v51, v4
	v_mov_b32_e32 v60, v4
	v_mov_b32_e32 v61, v4
	v_mov_b32_e32 v62, v4
	v_mov_b32_e32 v63, v4
	v_mov_b32_e32 v64, v4
	v_mov_b32_e32 v65, v4
	v_mov_b32_e32 v66, v4
	v_mov_b32_e32 v67, v4
	v_mov_b32_e32 v68, v4
	v_mov_b32_e32 v69, v4
	v_mov_b32_e32 v70, v4
	v_mov_b32_e32 v71, v4
	v_mov_b32_e32 v72, v4
	v_mov_b32_e32 v73, v4
	v_mov_b32_e32 v74, v4
	v_mov_b32_e32 v75, v4
	v_mov_b32_e32 v84, v4
	v_mov_b32_e32 v85, v4
	v_mov_b32_e32 v86, v4
	v_mov_b32_e32 v87, v4
	v_mov_b32_e32 v88, v4
	v_mov_b32_e32 v89, v4
	v_mov_b32_e32 v90, v4
	v_mov_b32_e32 v91, v4
	v_mov_b32_e32 v100, v4
	v_mov_b32_e32 v101, v4
	v_mov_b32_e32 v102, v4
	v_mov_b32_e32 v103, v4
	v_mov_b32_e32 v104, v4
	v_mov_b32_e32 v105, v4
	v_mov_b32_e32 v106, v4
	v_mov_b32_e32 v107, v4
	v_mov_b32_e32 v116, v4
	v_mov_b32_e32 v117, v4
	v_mov_b32_e32 v118, v4
	v_mov_b32_e32 v119, v4
	v_mov_b32_e32 v120, v4
	v_mov_b32_e32 v121, v4
	v_mov_b32_e32 v122, v4
	v_mov_b32_e32 v123, v4
	v_mov_b32_e32 v76, v4
	v_mov_b32_e32 v77, v4
	v_mov_b32_e32 v78, v4
	v_mov_b32_e32 v79, v4
	v_mov_b32_e32 v80, v4
	v_mov_b32_e32 v81, v4
	v_mov_b32_e32 v82, v4
	v_mov_b32_e32 v83, v4
	v_mov_b32_e32 v92, v4
	v_mov_b32_e32 v93, v4
	v_mov_b32_e32 v94, v4
	v_mov_b32_e32 v95, v4
	v_mov_b32_e32 v96, v4
	v_mov_b32_e32 v97, v4
	v_mov_b32_e32 v98, v4
	v_mov_b32_e32 v99, v4
	v_mov_b32_e32 v108, v4
	v_mov_b32_e32 v109, v4
	v_mov_b32_e32 v110, v4
	v_mov_b32_e32 v111, v4
	v_mov_b32_e32 v112, v4
	v_mov_b32_e32 v113, v4
	v_mov_b32_e32 v114, v4
	v_mov_b32_e32 v115, v4
	v_mov_b32_e32 v124, v4
	v_mov_b32_e32 v125, v4
	v_mov_b32_e32 v126, v4
	v_mov_b32_e32 v127, v4
	v_mov_b32_e32 v128, v4
	v_mov_b32_e32 v129, v4
	v_mov_b32_e32 v130, v4
	v_mov_b32_e32 v131, v4
	.p2alignl 6, 3212836864

.LBB0_558:
	s_ashr_i32 s49, s48, 31
	s_lshl_b64 s[36:37], s[48:49], 15
	s_add_u32 s54, s2, s36
	s_addc_u32 s55, s19, s37
	s_and_b64 s[36:37], s[42:43], exec
	s_cselect_b32 s36, s55, s35
	s_cselect_b32 s37, s54, s34
	s_add_u32 s49, s34, 0x80000
	s_addc_u32 s97, s35, 0
	s_add_u32 s42, s56, 0x80
	v_mov_b32_e32 v4, 0
	s_addc_u32 s43, s57, 0
	s_mov_b32 s34, 0
	s_waitcnt lgkmcnt(0)
	v_mov_b32_e32 v5, v4
	v_mov_b32_e32 v6, v4
	v_mov_b32_e32 v7, v4
	v_mov_b32_e32 v8, v4
	v_mov_b32_e32 v9, v4
	v_mov_b32_e32 v10, v4
	v_mov_b32_e32 v11, v4
	v_mov_b32_e32 v20, v4
	v_mov_b32_e32 v21, v4
	v_mov_b32_e32 v22, v4
	v_mov_b32_e32 v23, v4
	v_mov_b32_e32 v24, v4
	v_mov_b32_e32 v25, v4
	v_mov_b32_e32 v26, v4
	v_mov_b32_e32 v27, v4
	v_mov_b32_e32 v36, v4
	v_mov_b32_e32 v37, v4
	v_mov_b32_e32 v38, v4
	v_mov_b32_e32 v39, v4
	v_mov_b32_e32 v40, v4
	v_mov_b32_e32 v41, v4
	v_mov_b32_e32 v42, v4
	v_mov_b32_e32 v43, v4
	v_mov_b32_e32 v52, v4
	v_mov_b32_e32 v53, v4
	v_mov_b32_e32 v54, v4
	v_mov_b32_e32 v55, v4
	v_mov_b32_e32 v56, v4
	v_mov_b32_e32 v57, v4
	v_mov_b32_e32 v58, v4
	v_mov_b32_e32 v59, v4
	v_mov_b32_e32 v12, v4
	v_mov_b32_e32 v13, v4
	v_mov_b32_e32 v14, v4
	v_mov_b32_e32 v15, v4
	v_mov_b32_e32 v16, v4
	v_mov_b32_e32 v17, v4
	v_mov_b32_e32 v18, v4
	v_mov_b32_e32 v19, v4
	v_mov_b32_e32 v28, v4
	v_mov_b32_e32 v29, v4
	v_mov_b32_e32 v30, v4
	v_mov_b32_e32 v31, v4
	v_mov_b32_e32 v32, v4
	v_mov_b32_e32 v33, v4
	v_mov_b32_e32 v34, v4
	v_mov_b32_e32 v35, v4
	v_mov_b32_e32 v44, v4
	v_mov_b32_e32 v45, v4
	v_mov_b32_e32 v46, v4
	v_mov_b32_e32 v47, v4
	v_mov_b32_e32 v48, v4
	v_mov_b32_e32 v49, v4
	v_mov_b32_e32 v50, v4
	v_mov_b32_e32 v51, v4
	v_mov_b32_e32 v60, v4
	v_mov_b32_e32 v61, v4
	v_mov_b32_e32 v62, v4
	v_mov_b32_e32 v63, v4
	v_mov_b32_e32 v64, v4
	v_mov_b32_e32 v65, v4
	v_mov_b32_e32 v66, v4
	v_mov_b32_e32 v67, v4
	v_mov_b32_e32 v68, v4
	v_mov_b32_e32 v69, v4
	v_mov_b32_e32 v70, v4
	v_mov_b32_e32 v71, v4
	v_mov_b32_e32 v72, v4
	v_mov_b32_e32 v73, v4
	v_mov_b32_e32 v74, v4
	v_mov_b32_e32 v75, v4
	v_mov_b32_e32 v84, v4
	v_mov_b32_e32 v85, v4
	v_mov_b32_e32 v86, v4
	v_mov_b32_e32 v87, v4
	v_mov_b32_e32 v88, v4
	v_mov_b32_e32 v89, v4
	v_mov_b32_e32 v90, v4
	v_mov_b32_e32 v91, v4
	v_mov_b32_e32 v100, v4
	v_mov_b32_e32 v101, v4
	v_mov_b32_e32 v102, v4
	v_mov_b32_e32 v103, v4
	v_mov_b32_e32 v104, v4
	v_mov_b32_e32 v105, v4
	v_mov_b32_e32 v106, v4
	v_mov_b32_e32 v107, v4
	v_mov_b32_e32 v128, v4
	v_mov_b32_e32 v129, v4
	v_mov_b32_e32 v130, v4
	v_mov_b32_e32 v131, v4
	v_mov_b32_e32 v132, v4
	v_mov_b32_e32 v133, v4
	v_mov_b32_e32 v134, v4
	v_mov_b32_e32 v135, v4
	v_mov_b32_e32 v76, v4
	v_mov_b32_e32 v77, v4
	v_mov_b32_e32 v78, v4
	v_mov_b32_e32 v79, v4
	v_mov_b32_e32 v80, v4
	v_mov_b32_e32 v81, v4
	v_mov_b32_e32 v82, v4
	v_mov_b32_e32 v83, v4
	v_mov_b32_e32 v92, v4
	v_mov_b32_e32 v93, v4
	v_mov_b32_e32 v94, v4
	v_mov_b32_e32 v95, v4
	v_mov_b32_e32 v96, v4
	v_mov_b32_e32 v97, v4
	v_mov_b32_e32 v98, v4
	v_mov_b32_e32 v99, v4
	v_mov_b32_e32 v108, v4
	v_mov_b32_e32 v109, v4
	v_mov_b32_e32 v110, v4
	v_mov_b32_e32 v111, v4
	v_mov_b32_e32 v112, v4
	v_mov_b32_e32 v113, v4
	v_mov_b32_e32 v114, v4
	v_mov_b32_e32 v115, v4
	v_mov_b32_e32 v140, v4
	v_mov_b32_e32 v141, v4
	v_mov_b32_e32 v142, v4
	v_mov_b32_e32 v143, v4
	v_mov_b32_e32 v144, v4
	v_mov_b32_e32 v145, v4
	v_mov_b32_e32 v146, v4
	v_mov_b32_e32 v147, v4
	.p2alignl 6, 3212836864
